# phase F boundary-row fix-up: waves 0-2 issue both items loads before first use (single memory round trip)
# baseline (speedup 1.0000x reference)
; __global__ void __launch_bounds__(NTHREADS, 2) mk_fwd(Args args) {
;     ...
;             const Epi E{ws, out, args.in[5] + (size_t)layer * NPROJ, args.in[st == 4 ? 12 : 20] + (size_t)layer * DM, args.in[st == 4 ? 13 : 21] + (size_t)layer * DM,
;                         (unsigned*)(ws + WS_CTL) + CW_SEAM + (2 * layer + (st == 4 ? 0 : 1)) * SEAM_BANK, args.in[15] + (size_t)layer * 3 * DFF, args.in[16] + (size_t)layer * DFF, 0, (layer == DEPTH - 1 && st == 8) ? 1 : 0, st == 8 ? 1 : 0};
;             if (st == 8) {
;                 int pm_, pn_; pg8::tile_order(64, 4, bx, pm_, pn_);
;                 f16* A2 = (f16*)(ws + B_VAL); const float* GB = (const float*)(ws + B_SIDE); const float* YP = (const float*)(ws + B_SIDE + SIDE_STRIDE); const float* VB = (const float*)(ws + B_SIDE + 2 * SIDE_STRIDE);
;                 const float* cw = args.in[15] + (size_t)layer * 3 * DFF;
;                 constexpr int NCH = DFF / 8;
;                 for (int it = tid; it < 2 * NCH; it += NTHREADS) {
;                     const int fc = it % NCH, which = it / NCH, pm = pm_, pw = pm * 2 + which, f0 = fc * 8;
;                     if ((which == 0 && (pm & 7) == 0) || (which == 1 && (pm & 7) == 7)) continue;
.LBB0_133:
	s_and_b64 s[2:3], s[8:9], exec
	s_movk_i32 s2, 0xa0
	s_cselect_b32 s2, 0x60, s2
	s_add_u32 s2, s66, s2
	s_addc_u32 s3, s67, 0
	s_load_dwordx2 s[2:3], s[2:3], 0x0
	v_writelane_b32 v255, s8, 7
	s_and_b64 s[6:7], s[8:9], exec
	s_movk_i32 s6, 0x68
	s_cselect_b32 s6, s6, 0xa8
	v_writelane_b32 v255, s9, 8
	s_add_u32 s6, s66, s6
	s_addc_u32 s7, s67, 0
	s_waitcnt lgkmcnt(0)
	v_writelane_b32 v255, s2, 9
	v_readlane_b32 s8, v254, 24
	v_readlane_b32 s10, v254, 26
	v_writelane_b32 v255, s3, 10
	s_load_dwordx2 s[2:3], s[6:7], 0x0
	v_readlane_b32 s11, v254, 27
	v_cndmask_b32_e64 v0, 0, 1, s[26:27]
	v_cmp_ne_u32_e64 s[28:29], 1, v0
	v_readlane_b32 s9, v254, 25
	s_waitcnt lgkmcnt(0)
	v_writelane_b32 v255, s2, 11
	v_readlane_b32 s12, v254, 28
	v_readlane_b32 s13, v254, 29
	v_writelane_b32 v255, s3, 12
	s_mul_i32 s2, s72, 0x8400
	s_add_u32 s30, s10, s2
	s_addc_u32 s31, s11, 0
	s_andn2_b64 vcc, exec, s[26:27]
	v_readlane_b32 s14, v254, 30
	v_readlane_b32 s15, v254, 31
	s_cbranch_vccnz .LBB0_141
	v_add_u32_e32 v8, s94, v167
	s_movk_i32 s2, 0x2c0
	v_cmp_gt_i32_e32 vcc, s2, v8
	s_and_saveexec_b64 s[2:3], vcc
	s_cbranch_execz .LBB0_140
	v_lshlrev_b32_e32 v9, 3, v8
	s_cmp_lt_u32 s94, 0xc0
	s_cbranch_scc0 .Lfix_single
	s_and_b64 vcc, exec, s[20:21]
	s_cbranch_vccnz .Lfix_single
	v_readlane_b32 s12, v254, 12
	v_readlane_b32 s13, v254, 13
	s_and_b64 vcc, exec, s[12:13]
	s_cbranch_vccnz .Lfix_dual
.Lfix_single:
	s_mov_b64 s[8:9], 0
	s_branch .LBB0_137
.LBB0_136:
	s_or_b64 exec, exec, s[10:11]
	s_movk_i32 s6, 0xbf
	v_cmp_lt_i32_e32 vcc, s6, v8
	v_add_u32_e32 v9, 0x1000, v9
	s_or_b64 s[8:9], vcc, s[8:9]
	v_add_u32_e32 v8, 0x200, v8
	s_andn2_b64 exec, exec, s[8:9]
	s_cbranch_execz .LBB0_140

; __global__ void __launch_bounds__(NTHREADS, 2) mk_fwd(Args args) {
;     ...
;                 for (int it = tid; it < 2 * NCH; it += NTHREADS) {
;                     const int fc = it % NCH, which = it / NCH, pm = pm_, pw = pm * 2 + which, f0 = fc * 8;
;                     if ((which == 0 && (pm & 7) == 0) || (which == 1 && (pm & 7) == 7)) continue;
;                     const float* nb = which ? GB + (size_t)((pm + 1) * 2 + 0) * DFF + f0 : GB + (size_t)((pm - 1) * 2 + 1) * DFF + f0;
;                     const float* wt = cw + (which ? 2 * DFF : 0) + f0; const float* yp = YP + (size_t)pw * DFF + f0; const float* vb = VB + (size_t)pw * DFF + f0;
;                     float r8[8];
; #pragma unroll
;                     for (int q = 0; q < 4; ++q) { const f32x2 y = {yp[2 * q] + wt[2 * q] * nb[2 * q], yp[2 * q + 1] + wt[2 * q + 1] * nb[2 * q + 1]}; const f32x2 g = gelu_pk(y); r8[2 * q] = g.x * vb[2 * q]; r8[2 * q + 1] = g.y * vb[2 * q + 1]; }
.Lfix_dual:
	s_mov_b64 vcc, -1
	s_mov_b32 s6, 0x2e8ba2e9
	v_mul_hi_i32 v0, v8, s6
	v_lshrrev_b32_e32 v1, 31, v0
	v_ashrrev_i32_e32 v0, 6, v0
	v_add_u32_e32 v0, v0, v1
	v_mul_i32_i24_e32 v1, 0x160, v0
	v_add_u32_e32 v30, s44, v0
	v_lshlrev_b32_e32 v0, 3, v1
	v_readlane_b32 s6, v251, 22
	v_sub_u32_e32 v4, v9, v0
	v_cndmask_b32_e64 v0, 2, -1, vcc
	v_readlane_b32 s7, v251, 23
	v_add_u32_e32 v2, s44, v0
	s_movk_i32 s12, 0x2c00
	v_mov_b64_e32 v[0:1], s[6:7]
	v_mad_i64_i32 v[0:1], s[6:7], v2, s12, v[0:1]
	v_readlane_b32 s6, v251, 24
	v_readlane_b32 s7, v251, 25
	v_ashrrev_i32_e32 v5, 31, v4
	v_cndmask_b32_e64 v32, v233, 0, vcc
	v_mov_b64_e32 v[10:11], s[6:7]
	v_lshlrev_b64 v[2:3], 2, v[4:5]
	v_mad_i64_i32 v[10:11], s[6:7], v30, s12, v[10:11]
	v_lshl_add_u64 v[6:7], s[30:31], 0, v[32:33]
	v_lshl_add_u64 v[14:15], v[10:11], 0, v[2:3]
	v_lshl_add_u64 v[0:1], v[0:1], 0, v[2:3]
	v_lshl_add_u64 v[6:7], v[6:7], 0, v[2:3]
	global_load_dwordx4 v[10:13], v[14:15], off offset:16
	s_nop 0
	global_load_dwordx4 v[14:17], v[14:15], off
	s_nop 0
	global_load_dwordx4 v[18:21], v[0:1], off
	global_load_dwordx4 v[22:25], v[6:7], off
	global_load_dwordx4 v[26:29], v[6:7], off offset:16
	global_load_dwordx4 v[34:37], v[0:1], off offset:16
	v_readlane_b32 s6, v251, 26
	v_readlane_b32 s7, v251, 27
	s_mov_b32 s24, 0xbf38aa3b
	s_mov_b32 s14, 0x3f07dc22
	v_mov_b64_e32 v[0:1], s[6:7]
	v_mad_i64_i32 v[0:1], s[6:7], v30, s12, v[0:1]
	v_lshl_add_u64 v[0:1], v[0:1], 0, v[2:3]
	global_load_dwordx4 v[38:41], v[0:1], off
	s_nop 0
	global_load_dwordx4 v[0:3], v[0:1], off offset:16
	s_mov_b32 s12, 0x3e6d3388
	s_mov_b32 s6, 0xbf3a00e3
	v_mov_b64_e32 v[6:7], s[6:7]
	s_mov_b32 s16, 0x3f35f0e3
	s_mov_b32 s18, 0xbe11a98e
	s_mov_b32 s22, 0x3e027906
	v_add_u32_e32 v52, 0x200, v8
	v_add_u32_e32 v53, 0x1000, v9
	v_mov_b32_e32 v77, 0
	s_mov_b64 vcc, 0
	s_mov_b32 s6, 0x2e8ba2e9
	v_mul_hi_i32 v44, v52, s6
	v_lshrrev_b32_e32 v45, 31, v44
	v_ashrrev_i32_e32 v44, 6, v44
	v_add_u32_e32 v44, v44, v45
	v_mul_i32_i24_e32 v45, 0x160, v44
	v_add_u32_e32 v74, s44, v44
	v_lshlrev_b32_e32 v44, 3, v45
	v_readlane_b32 s6, v251, 22
	v_sub_u32_e32 v48, v53, v44
	v_cndmask_b32_e64 v44, 2, -1, vcc
	v_readlane_b32 s7, v251, 23
	v_add_u32_e32 v46, s44, v44
	s_movk_i32 s12, 0x2c00
	v_mov_b64_e32 v[44:45], s[6:7]
	v_mad_i64_i32 v[44:45], s[6:7], v46, s12, v[44:45]
	v_readlane_b32 s6, v251, 24
	v_readlane_b32 s7, v251, 25
	v_ashrrev_i32_e32 v49, 31, v48
	v_cndmask_b32_e64 v76, v233, 0, vcc
	v_mov_b64_e32 v[54:55], s[6:7]
	v_lshlrev_b64 v[46:47], 2, v[48:49]
	v_mad_i64_i32 v[54:55], s[6:7], v74, s12, v[54:55]
	v_lshl_add_u64 v[50:51], s[30:31], 0, v[76:77]
	v_lshl_add_u64 v[58:59], v[54:55], 0, v[46:47]
	v_lshl_add_u64 v[44:45], v[44:45], 0, v[46:47]
	v_lshl_add_u64 v[50:51], v[50:51], 0, v[46:47]
	global_load_dwordx4 v[54:57], v[58:59], off offset:16
	s_nop 0
	global_load_dwordx4 v[58:61], v[58:59], off
	s_nop 0
	global_load_dwordx4 v[62:65], v[44:45], off
	global_load_dwordx4 v[66:69], v[50:51], off
	global_load_dwordx4 v[70:73], v[50:51], off offset:16
	global_load_dwordx4 v[78:81], v[44:45], off offset:16
	v_readlane_b32 s6, v251, 26
	v_readlane_b32 s7, v251, 27
	s_mov_b32 s24, 0xbf38aa3b
	s_mov_b32 s14, 0x3f07dc22
	v_mov_b64_e32 v[44:45], s[6:7]
	v_mad_i64_i32 v[44:45], s[6:7], v74, s12, v[44:45]
	v_lshl_add_u64 v[44:45], v[44:45], 0, v[46:47]
	global_load_dwordx4 v[82:85], v[44:45], off
	s_nop 0
	global_load_dwordx4 v[44:47], v[44:45], off offset:16
	s_mov_b32 s12, 0x3e6d3388
	s_mov_b32 s6, 0xbf3a00e3
	v_mov_b64_e32 v[50:51], s[6:7]
	s_mov_b32 s16, 0x3f35f0e3
	s_mov_b32 s18, 0xbe11a98e
	s_mov_b32 s22, 0x3e027906
	s_waitcnt vmcnt(8)
	s_mov_b64 vcc, -1
	v_pk_fma_f32 v[14:15], v[22:23], v[18:19], v[14:15]
	v_pk_fma_f32 v[16:17], v[24:25], v[20:21], v[16:17]
	v_and_b32_e32 v19, 0x7fffffff, v15
	v_and_b32_e32 v18, 0x7fffffff, v14
	v_and_b32_e32 v23, 0x7fffffff, v17
	v_and_b32_e32 v22, 0x7fffffff, v16
	v_pk_fma_f32 v[18:19], v[18:19], s[12:13], 1.0 op_sel_hi:[1,0,0]
	v_pk_fma_f32 v[22:23], v[22:23], s[12:13], 1.0 op_sel_hi:[1,0,0]
	v_rcp_f32_e32 v18, v18
	v_rcp_f32_e32 v19, v19
	s_nop 0
	v_pk_fma_f32 v[10:11], v[26:27], v[34:35], v[10:11]
	v_rcp_f32_e32 v22, v22
	v_rcp_f32_e32 v23, v23
	v_and_b32_e32 v27, 0x7fffffff, v11
	v_and_b32_e32 v26, 0x7fffffff, v10
	v_pk_mul_f32 v[20:21], v[14:15], v[14:15]
	v_pk_fma_f32 v[26:27], v[26:27], s[12:13], 1.0 op_sel_hi:[1,0,0]
	v_pk_mul_f32 v[24:25], v[16:17], v[16:17]
	v_pk_mul_f32 v[20:21], v[20:21], s[24:25] op_sel_hi:[1,0]
	v_rcp_f32_e32 v26, v26
	v_rcp_f32_e32 v27, v27
	v_pk_fma_f32 v[34:35], v[18:19], s[14:15], v[6:7] op_sel_hi:[1,0,0]
	v_pk_fma_f32 v[12:13], v[28:29], v[36:37], v[12:13]
	v_pk_mul_f32 v[24:25], v[24:25], s[24:25] op_sel_hi:[1,0]
	v_exp_f32_e32 v20, v20
	v_exp_f32_e32 v21, v21
	v_pk_fma_f32 v[36:37], v[22:23], s[14:15], v[6:7] op_sel_hi:[1,0,0]
	v_pk_fma_f32 v[34:35], v[18:19], v[34:35], s[16:17] op_sel_hi:[1,1,0]
	v_exp_f32_e32 v24, v24
	v_exp_f32_e32 v25, v25
	v_pk_fma_f32 v[36:37], v[22:23], v[36:37], s[16:17] op_sel_hi:[1,1,0]
	v_pk_fma_f32 v[34:35], v[18:19], v[34:35], s[18:19] op_sel_hi:[1,1,0]
	v_pk_mul_f32 v[28:29], v[10:11], v[10:11]
	v_pk_fma_f32 v[36:37], v[22:23], v[36:37], s[18:19] op_sel_hi:[1,1,0]
	v_pk_fma_f32 v[34:35], v[18:19], v[34:35], s[22:23] op_sel_hi:[1,1,0]
	v_pk_mul_f32 v[28:29], v[28:29], s[24:25] op_sel_hi:[1,0]
	v_pk_fma_f32 v[42:43], v[26:27], s[14:15], v[6:7] op_sel_hi:[1,0,0]
	v_pk_fma_f32 v[36:37], v[22:23], v[36:37], s[22:23] op_sel_hi:[1,1,0]
	v_pk_mul_f32 v[18:19], v[18:19], v[34:35]
	v_exp_f32_e32 v28, v28
	v_exp_f32_e32 v29, v29
	v_pk_fma_f32 v[42:43], v[26:27], v[42:43], s[16:17] op_sel_hi:[1,1,0]
; template <unsigned D> __device__ __forceinline__ u32x4 rd8(u32x4 w) { w.x = rd<D>(w.x); w.y = rd<D>(w.y); w.z = rd<D>(w.z); w.w = rd<D>(w.w); return w; }
; __global__ void __launch_bounds__(NTHREADS, 2) mk_fwd(Args args) {
;     ...
;                     for (int q = 0; q < 4; ++q) { const f32x2 y = {yp[2 * q] + wt[2 * q] * nb[2 * q], yp[2 * q + 1] + wt[2 * q + 1] * nb[2 * q + 1]}; const f32x2 g = gelu_pk(y); r8[2 * q] = g.x * vb[2 * q]; r8[2 * q + 1] = g.y * vb[2 * q + 1]; }
;                     u32x4 o; o.x = pk_f16(r8[0], r8[1]); o.y = pk_f16(r8[2], r8[3]); o.z = pk_f16(r8[4], r8[5]); o.w = pk_f16(r8[6], r8[7]); o = rd8<D_A2>(o);
;                     *(u32x4*)(A2 + (size_t)(pm * 256 + (which ? 255 : 0)) * DFF + f0) = o;
	v_pk_mul_f32 v[22:23], v[22:23], v[36:37]
	v_pk_mul_f32 v[18:19], v[20:21], v[18:19]
	v_pk_fma_f32 v[42:43], v[26:27], v[42:43], s[18:19] op_sel_hi:[1,1,0]
	v_pk_mul_f32 v[20:21], v[24:25], v[22:23]
	v_pk_mul_f32 v[24:25], v[14:15], v[18:19]
	v_pk_fma_f32 v[18:19], v[14:15], v[18:19], v[14:15] neg_lo:[1,0,0] neg_hi:[1,0,0]
	v_cmp_gt_f32_e64 s[6:7], 0, v15
	v_pk_fma_f32 v[42:43], v[26:27], v[42:43], s[22:23] op_sel_hi:[1,1,0]
	v_and_b32_e32 v31, 0x7fffffff, v13
	v_cndmask_b32_e64 v15, v19, v25, s[6:7]
	v_cmp_gt_f32_e64 s[6:7], 0, v14
	v_pk_mul_f32 v[26:27], v[26:27], v[42:43]
	v_and_b32_e32 v30, 0x7fffffff, v12
	v_cndmask_b32_e64 v14, v18, v24, s[6:7]
	v_pk_mul_f32 v[22:23], v[28:29], v[26:27]
	v_pk_mul_f32 v[26:27], v[16:17], v[20:21]
	v_pk_fma_f32 v[20:21], v[16:17], v[20:21], v[16:17] neg_lo:[1,0,0] neg_hi:[1,0,0]
	v_cmp_gt_f32_e64 s[6:7], 0, v17
	s_nop 0
	v_pk_mul_f32 v[14:15], v[38:39], v[14:15]
	v_pk_mul_f32 v[28:29], v[10:11], v[22:23]
	v_cndmask_b32_e64 v17, v21, v27, s[6:7]
	v_cmp_gt_f32_e64 s[6:7], 0, v16
	v_cvt_pk_f16_f32 v18, v14, v15
	v_pk_fma_f32 v[14:15], v[30:31], s[12:13], 1.0 op_sel_hi:[1,0,0]
	v_pk_fma_f32 v[22:23], v[10:11], v[22:23], v[10:11] neg_lo:[1,0,0] neg_hi:[1,0,0]
	v_cndmask_b32_e64 v16, v20, v26, s[6:7]
	v_cmp_gt_f32_e64 s[6:7], 0, v11
	v_rcp_f32_e32 v14, v14
	v_rcp_f32_e32 v15, v15
	v_cndmask_b32_e64 v11, v23, v29, s[6:7]
	v_cmp_gt_f32_e64 s[6:7], 0, v10
	v_pk_mul_f32 v[16:17], v[40:41], v[16:17]
	s_nop 0
	v_cndmask_b32_e64 v10, v22, v28, s[6:7]
	s_nop 0
	v_pk_mul_f32 v[0:1], v[0:1], v[10:11]
	v_cmp_gt_f32_e64 s[6:7], 0, v13
	v_cvt_pk_f16_f32 v10, v0, v1
	v_pk_fma_f32 v[0:1], v[14:15], s[14:15], v[6:7] op_sel_hi:[1,0,0]
	v_pk_mul_f32 v[6:7], v[12:13], v[12:13]
	v_pk_fma_f32 v[0:1], v[14:15], v[0:1], s[16:17] op_sel_hi:[1,1,0]
	v_pk_mul_f32 v[6:7], v[6:7], s[24:25] op_sel_hi:[1,0]
	v_pk_fma_f32 v[0:1], v[14:15], v[0:1], s[18:19] op_sel_hi:[1,1,0]
	v_exp_f32_e32 v6, v6
	v_exp_f32_e32 v7, v7
	v_pk_fma_f32 v[0:1], v[14:15], v[0:1], s[22:23] op_sel_hi:[1,1,0]
	v_cvt_pk_f16_f32 v16, v16, v17
	v_pk_mul_f32 v[0:1], v[14:15], v[0:1]
	s_nop 0
	v_pk_mul_f32 v[0:1], v[6:7], v[0:1]
	s_nop 0
	v_pk_mul_f32 v[6:7], v[12:13], v[0:1]
	v_pk_fma_f32 v[0:1], v[12:13], v[0:1], v[12:13] neg_lo:[1,0,0] neg_hi:[1,0,0]
	s_nop 0
	v_cndmask_b32_e64 v1, v1, v7, s[6:7]
	v_cmp_gt_f32_e64 s[6:7], 0, v12
	s_nop 1
	v_cndmask_b32_e64 v0, v0, v6, s[6:7]
	v_readlane_b32 s6, v253, 13
	v_pk_mul_f32 v[0:1], v[2:3], v[0:1]
	v_cndmask_b32_e64 v6, v250, 0, vcc
	v_readlane_b32 s7, v253, 14
	v_cvt_pk_f16_f32 v3, v0, v1
	v_add_u32_e32 v2, 0x40004, v10
	v_or_b32_e32 v10, s50, v6
	v_mov_b64_e32 v[6:7], s[6:7]
	s_movk_i32 s6, 0x1600
	v_add_u32_e32 v0, 0x40004, v18
	v_add_u32_e32 v1, 0x40004, v16
	v_add_u32_e32 v3, 0x40004, v3
	v_mad_i64_i32 v[6:7], s[6:7], v10, s6, v[6:7]
	v_and_b32_e32 v0, 0xfff8fff8, v0
	v_and_b32_e32 v1, 0xfff8fff8, v1
	v_and_b32_e32 v2, 0xfff8fff8, v2
	v_and_b32_e32 v3, 0xfff8fff8, v3
	v_lshl_add_u64 v[4:5], v[4:5], 1, v[6:7]
	s_waitcnt vmcnt(0)
; template <unsigned D> __device__ __forceinline__ u32x4 rd8(u32x4 w) { w.x = rd<D>(w.x); w.y = rd<D>(w.y); w.z = rd<D>(w.z); w.w = rd<D>(w.w); return w; }
; __global__ void __launch_bounds__(NTHREADS, 2) mk_fwd(Args args) {
;     ...
;                     for (int q = 0; q < 4; ++q) { const f32x2 y = {yp[2 * q] + wt[2 * q] * nb[2 * q], yp[2 * q + 1] + wt[2 * q + 1] * nb[2 * q + 1]}; const f32x2 g = gelu_pk(y); r8[2 * q] = g.x * vb[2 * q]; r8[2 * q + 1] = g.y * vb[2 * q + 1]; }
;                     u32x4 o; o.x = pk_f16(r8[0], r8[1]); o.y = pk_f16(r8[2], r8[3]); o.z = pk_f16(r8[4], r8[5]); o.w = pk_f16(r8[6], r8[7]); o = rd8<D_A2>(o);
;                     *(u32x4*)(A2 + (size_t)(pm * 256 + (which ? 255 : 0)) * DFF + f0) = o;
	global_store_dwordx4 v[4:5], v[0:3], off
	s_mov_b64 vcc, 0
	v_pk_fma_f32 v[58:59], v[66:67], v[62:63], v[58:59]
	v_pk_fma_f32 v[60:61], v[68:69], v[64:65], v[60:61]
	v_and_b32_e32 v63, 0x7fffffff, v59
	v_and_b32_e32 v62, 0x7fffffff, v58
	v_and_b32_e32 v67, 0x7fffffff, v61
	v_and_b32_e32 v66, 0x7fffffff, v60
	v_pk_fma_f32 v[62:63], v[62:63], s[12:13], 1.0 op_sel_hi:[1,0,0]
	v_pk_fma_f32 v[66:67], v[66:67], s[12:13], 1.0 op_sel_hi:[1,0,0]
	v_rcp_f32_e32 v62, v62
	v_rcp_f32_e32 v63, v63
	s_nop 0
	v_pk_fma_f32 v[54:55], v[70:71], v[78:79], v[54:55]
	v_rcp_f32_e32 v66, v66
	v_rcp_f32_e32 v67, v67
	v_and_b32_e32 v71, 0x7fffffff, v55
	v_and_b32_e32 v70, 0x7fffffff, v54
	v_pk_mul_f32 v[64:65], v[58:59], v[58:59]
	v_pk_fma_f32 v[70:71], v[70:71], s[12:13], 1.0 op_sel_hi:[1,0,0]
	v_pk_mul_f32 v[68:69], v[60:61], v[60:61]
	v_pk_mul_f32 v[64:65], v[64:65], s[24:25] op_sel_hi:[1,0]
	v_rcp_f32_e32 v70, v70
	v_rcp_f32_e32 v71, v71
	v_pk_fma_f32 v[78:79], v[62:63], s[14:15], v[50:51] op_sel_hi:[1,0,0]
	v_pk_fma_f32 v[56:57], v[72:73], v[80:81], v[56:57]
	v_pk_mul_f32 v[68:69], v[68:69], s[24:25] op_sel_hi:[1,0]
	v_exp_f32_e32 v64, v64
	v_exp_f32_e32 v65, v65
	v_pk_fma_f32 v[80:81], v[66:67], s[14:15], v[50:51] op_sel_hi:[1,0,0]
	v_pk_fma_f32 v[78:79], v[62:63], v[78:79], s[16:17] op_sel_hi:[1,1,0]
	v_exp_f32_e32 v68, v68
	v_exp_f32_e32 v69, v69
	v_pk_fma_f32 v[80:81], v[66:67], v[80:81], s[16:17] op_sel_hi:[1,1,0]
	v_pk_fma_f32 v[78:79], v[62:63], v[78:79], s[18:19] op_sel_hi:[1,1,0]
	v_pk_mul_f32 v[72:73], v[54:55], v[54:55]
	v_pk_fma_f32 v[80:81], v[66:67], v[80:81], s[18:19] op_sel_hi:[1,1,0]
	v_pk_fma_f32 v[78:79], v[62:63], v[78:79], s[22:23] op_sel_hi:[1,1,0]
	v_pk_mul_f32 v[72:73], v[72:73], s[24:25] op_sel_hi:[1,0]
	v_pk_fma_f32 v[86:87], v[70:71], s[14:15], v[50:51] op_sel_hi:[1,0,0]
	v_pk_fma_f32 v[80:81], v[66:67], v[80:81], s[22:23] op_sel_hi:[1,1,0]
	v_pk_mul_f32 v[62:63], v[62:63], v[78:79]
	v_exp_f32_e32 v72, v72
	v_exp_f32_e32 v73, v73
	v_pk_fma_f32 v[86:87], v[70:71], v[86:87], s[16:17] op_sel_hi:[1,1,0]
	v_pk_mul_f32 v[66:67], v[66:67], v[80:81]
	v_pk_mul_f32 v[62:63], v[64:65], v[62:63]
	v_pk_fma_f32 v[86:87], v[70:71], v[86:87], s[18:19] op_sel_hi:[1,1,0]
	v_pk_mul_f32 v[64:65], v[68:69], v[66:67]
	v_pk_mul_f32 v[68:69], v[58:59], v[62:63]
	v_pk_fma_f32 v[62:63], v[58:59], v[62:63], v[58:59] neg_lo:[1,0,0] neg_hi:[1,0,0]
	v_cmp_gt_f32_e64 s[6:7], 0, v59
	v_pk_fma_f32 v[86:87], v[70:71], v[86:87], s[22:23] op_sel_hi:[1,1,0]
	v_and_b32_e32 v75, 0x7fffffff, v57
	v_cndmask_b32_e64 v59, v63, v69, s[6:7]
	v_cmp_gt_f32_e64 s[6:7], 0, v58
	v_pk_mul_f32 v[70:71], v[70:71], v[86:87]
	v_and_b32_e32 v74, 0x7fffffff, v56
	v_cndmask_b32_e64 v58, v62, v68, s[6:7]
	v_pk_mul_f32 v[66:67], v[72:73], v[70:71]
	v_pk_mul_f32 v[70:71], v[60:61], v[64:65]
	v_pk_fma_f32 v[64:65], v[60:61], v[64:65], v[60:61] neg_lo:[1,0,0] neg_hi:[1,0,0]
	v_cmp_gt_f32_e64 s[6:7], 0, v61
	s_nop 0
	v_pk_mul_f32 v[58:59], v[82:83], v[58:59]
	v_pk_mul_f32 v[72:73], v[54:55], v[66:67]
	v_cndmask_b32_e64 v61, v65, v71, s[6:7]
	v_cmp_gt_f32_e64 s[6:7], 0, v60
	v_cvt_pk_f16_f32 v62, v58, v59
	v_pk_fma_f32 v[58:59], v[74:75], s[12:13], 1.0 op_sel_hi:[1,0,0]
	v_pk_fma_f32 v[66:67], v[54:55], v[66:67], v[54:55] neg_lo:[1,0,0] neg_hi:[1,0,0]
	v_cndmask_b32_e64 v60, v64, v70, s[6:7]
	v_cmp_gt_f32_e64 s[6:7], 0, v55
	v_rcp_f32_e32 v58, v58
	v_rcp_f32_e32 v59, v59
	v_cndmask_b32_e64 v55, v67, v73, s[6:7]
	v_cmp_gt_f32_e64 s[6:7], 0, v54
	v_pk_mul_f32 v[60:61], v[84:85], v[60:61]
	s_nop 0
	v_cndmask_b32_e64 v54, v66, v72, s[6:7]
	s_nop 0
	v_pk_mul_f32 v[44:45], v[44:45], v[54:55]
	v_cmp_gt_f32_e64 s[6:7], 0, v57
	v_cvt_pk_f16_f32 v54, v44, v45
	v_pk_fma_f32 v[44:45], v[58:59], s[14:15], v[50:51] op_sel_hi:[1,0,0]
	v_pk_mul_f32 v[50:51], v[56:57], v[56:57]
	v_pk_fma_f32 v[44:45], v[58:59], v[44:45], s[16:17] op_sel_hi:[1,1,0]
	v_pk_mul_f32 v[50:51], v[50:51], s[24:25] op_sel_hi:[1,0]
	v_pk_fma_f32 v[44:45], v[58:59], v[44:45], s[18:19] op_sel_hi:[1,1,0]
	v_exp_f32_e32 v50, v50
	v_exp_f32_e32 v51, v51
	v_pk_fma_f32 v[44:45], v[58:59], v[44:45], s[22:23] op_sel_hi:[1,1,0]
	v_cvt_pk_f16_f32 v60, v60, v61
	v_pk_mul_f32 v[44:45], v[58:59], v[44:45]
	s_nop 0
	v_pk_mul_f32 v[44:45], v[50:51], v[44:45]
	s_nop 0
	v_pk_mul_f32 v[50:51], v[56:57], v[44:45]
	v_pk_fma_f32 v[44:45], v[56:57], v[44:45], v[56:57] neg_lo:[1,0,0] neg_hi:[1,0,0]
	s_nop 0
	v_cndmask_b32_e64 v45, v45, v51, s[6:7]
	v_cmp_gt_f32_e64 s[6:7], 0, v56
	s_nop 1
	v_cndmask_b32_e64 v44, v44, v50, s[6:7]
	v_readlane_b32 s6, v253, 13
	v_pk_mul_f32 v[44:45], v[46:47], v[44:45]
	v_cndmask_b32_e64 v50, v250, 0, vcc
	v_readlane_b32 s7, v253, 14
	v_cvt_pk_f16_f32 v47, v44, v45
	v_add_u32_e32 v46, 0x40004, v54
	v_or_b32_e32 v54, s50, v50
	v_mov_b64_e32 v[50:51], s[6:7]
	s_movk_i32 s6, 0x1600
	v_add_u32_e32 v44, 0x40004, v62
	v_add_u32_e32 v45, 0x40004, v60
	v_add_u32_e32 v47, 0x40004, v47
	v_mad_i64_i32 v[50:51], s[6:7], v54, s6, v[50:51]
	v_and_b32_e32 v44, 0xfff8fff8, v44
	v_and_b32_e32 v45, 0xfff8fff8, v45
	v_and_b32_e32 v46, 0xfff8fff8, v46
	v_and_b32_e32 v47, 0xfff8fff8, v47
	v_lshl_add_u64 v[48:49], v[48:49], 1, v[50:51]
	global_store_dwordx4 v[48:49], v[44:47], off
